# plus: rtab pair sum via DPP, EVIN q/k-norm row sums via permlane swaps
# speedup vs baseline: 1.0060x; 1.0060x over previous
.LBB0_109:
	v_cmp_gt_i64_e32 vcc, s[10:11], v[10:11]
	s_mov_b64 s[52:53], -1
	s_cbranch_vccnz .LBB0_108
	s_ashr_i32 s27, s10, 31
	s_lshr_b32 s27, s27, 29
	s_add_i32 s27, s10, s27
	s_ashr_i32 s33, s27, 3
	s_and_b32 s27, s27, -8
	s_sub_i32 s27, s10, s27
	s_cmp_lt_i32 s27, 0
	s_cselect_b32 s52, s24, 0x160
	s_mul_i32 s27, s27, s52
	s_add_i32 s27, s27, s33
	s_mul_hi_i32 s33, s27, 0x2e8ba2e9
	s_lshr_b32 s52, s33, 31
	s_ashr_i32 s33, s33, 4
	s_add_i32 s33, s33, s52
	s_lshl_b32 s52, s33, 2
	s_sub_i32 s53, 0x80, s52
	s_min_i32 s53, s53, 4
	s_mulk_i32 s33, 0x58
	s_sub_i32 s27, s27, s33
	v_cmp_lt_i32_e32 vcc, v19, v173
	s_and_b32 s27, s27, 3
	s_add_i32 s52, s52, s27
	v_cndmask_b32_e32 v28, v172, v19, vcc
	v_lshl_add_u32 v20, s52, 8, v16
	s_waitcnt lgkmcnt(0)
	v_ashrrev_i32_e32 v21, 31, v20
	v_lshlrev_b64 v[20:21], 6, v[20:21]
	v_lshl_add_u64 v[24:25], v[8:9], 0, v[20:21]
	global_load_dwordx4 v[20:23], v[24:25], off
	s_nop 0
	global_load_dwordx4 v[24:27], v[24:25], off offset:16
	s_waitcnt vmcnt(0)
	v_add_f32_e32 v20, v20, v21
	v_add_f32_e32 v21, v22, v23
	v_add_f32_e32 v22, v24, v25
	v_add_f32_e32 v23, v26, v27
	v_add_f32_e32 v20, v20, v21
	v_add_f32_e32 v21, v22, v23
	v_add_f32_e32 v20, v20, v21
	v_lshlrev_b32_e32 v21, 2, v28
	s_nop 1
	v_mov_b32_dpp v21, v20 quad_perm:[1,0,3,2] row_mask:0xf bank_mask:0xf
	s_and_saveexec_b64 s[52:53], s[6:7]
	s_cbranch_execz .LBB0_107
	s_waitcnt lgkmcnt(0)
	v_add_f32_e32 v20, v20, v21
	v_fmamk_f32 v20, v20, 0x3a800000, v18
	v_rsq_f32_e32 v20, v20
	v_add_u32_e32 v21, s26, v17
	ds_write_b32 v21, v20 offset:14336
	s_branch .LBB0_107

.LBB0_418:
	v_cmp_gt_i64_e32 vcc, s[10:11], v[10:11]
	s_mov_b64 s[52:53], -1
	s_cbranch_vccnz .LBB0_417
	s_ashr_i32 s17, s10, 31
	s_lshr_b32 s17, s17, 29
	s_add_i32 s17, s10, s17
	s_ashr_i32 s18, s17, 3
	s_and_b32 s17, s17, -8
	s_sub_i32 s17, s10, s17
	s_cmp_lt_i32 s17, 0
	s_movk_i32 s19, 0xa1
	s_cselect_b32 s19, s19, 0xa0
	s_mul_i32 s17, s17, s19
	s_add_i32 s17, s17, s18
	s_mul_hi_i32 s18, s17, 0x66666667
	s_lshr_b32 s19, s18, 31
	s_ashr_i32 s18, s18, 4
	s_add_i32 s18, s18, s19
	s_lshl_b32 s19, s18, 2
	s_sub_i32 s20, 0x80, s19
	s_min_i32 s20, s20, 4
	s_mul_i32 s18, s18, 40
	s_sub_i32 s17, s17, s18
	v_cmp_lt_i32_e32 vcc, v19, v155
	s_and_b32 s17, s17, 3
	s_add_i32 s19, s19, s17
	v_cndmask_b32_e32 v28, v149, v19, vcc
	v_lshl_add_u32 v20, s19, 8, v16
	s_waitcnt lgkmcnt(0)
	v_ashrrev_i32_e32 v21, 31, v20
	v_lshlrev_b64 v[20:21], 6, v[20:21]
	v_lshl_add_u64 v[24:25], v[8:9], 0, v[20:21]
	global_load_dwordx4 v[20:23], v[24:25], off
	s_nop 0
	global_load_dwordx4 v[24:27], v[24:25], off offset:16
	s_waitcnt vmcnt(0)
	v_add_f32_e32 v20, v20, v21
	v_add_f32_e32 v21, v22, v23
	v_add_f32_e32 v22, v24, v25
	v_add_f32_e32 v23, v26, v27
	v_add_f32_e32 v20, v20, v21
	v_add_f32_e32 v21, v22, v23
	v_add_f32_e32 v20, v20, v21
	v_lshlrev_b32_e32 v21, 2, v28
	s_nop 1
	v_mov_b32_dpp v21, v20 quad_perm:[1,0,3,2] row_mask:0xf bank_mask:0xf
	s_and_saveexec_b64 s[52:53], s[8:9]
	s_cbranch_execz .LBB0_416
	s_waitcnt lgkmcnt(0)
	v_add_f32_e32 v20, v20, v21
	v_fmamk_f32 v20, v20, 0x3a800000, v18
	v_rsq_f32_e32 v20, v20
	v_add_u32_e32 v21, s14, v17
	ds_write_b32 v21, v20 offset:14336
	s_branch .LBB0_416

.LBB0_447:
	s_andn2_b64 vcc, exec, s[6:7]
	s_cbranch_vccnz .LBB0_449
	s_cmp_gt_u32 s92, 5
	s_cselect_b64 s[6:7], -1, 0
	s_lshl_b32 s14, s92, 2
	s_and_b32 s16, s14, 4
	s_and_b64 s[14:15], s[6:7], exec
	s_mov_b64 s[14:15], s[26:27]
	v_readlane_b32 s20, v254, 0
	v_readlane_b32 s36, v254, 29
	v_readlane_b32 s21, v254, 1
	v_readlane_b32 s26, v254, 6
	v_readlane_b32 s27, v254, 7
	v_readlane_b32 s50, v254, 43
	v_readlane_b32 s51, v254, 44
	s_mov_b64 s[26:27], s[14:15]
	s_cselect_b32 s15, s21, s51
	s_cselect_b32 s14, s20, s50
	v_lshlrev_b32_e32 v180, 2, v148
	global_load_dwordx4 v[128:131], v180, s[14:15] offset:16
	global_load_dwordx4 v[134:137], v180, s[14:15]
	v_cndmask_b32_e64 v150, v211, 1.0, s[6:7]
	s_waitcnt lgkmcnt(0)
	v_pk_mul_f32 v[214:215], v[118:119], v[176:177] op_sel_hi:[1,0]
	v_pk_mul_f32 v[216:217], v[116:117], v[176:177] op_sel_hi:[1,0]
	v_pk_mul_f32 v[196:197], v[112:113], v[176:177] op_sel_hi:[1,0]
	s_mov_b32 s36, 0x40000
	v_readlane_b32 s37, v254, 30
	s_mov_b32 s37, 0x48000
	v_readlane_b32 s38, v254, 31
	s_mov_b32 s38, 0x50000
	v_readlane_b32 s22, v254, 2
	v_readlane_b32 s23, v254, 3
	v_readlane_b32 s24, v254, 4
	v_readlane_b32 s25, v254, 5
	v_readlane_b32 s39, v254, 32
	v_readlane_b32 s40, v254, 33
	v_readlane_b32 s41, v254, 34
	v_readlane_b32 s42, v254, 35
	v_readlane_b32 s43, v254, 36
	v_readlane_b32 s44, v254, 37
	v_readlane_b32 s45, v254, 38
	v_readlane_b32 s46, v254, 39
	v_readlane_b32 s47, v254, 40
	v_readlane_b32 s48, v254, 41
	v_readlane_b32 s49, v254, 42
	s_waitcnt vmcnt(0)
	v_pk_mul_f32 v[138:139], v[150:151], v[136:137] op_sel_hi:[0,1]
	v_pk_mul_f32 v[178:179], v[150:151], v[134:135] op_sel_hi:[0,1]
	v_pk_mul_f32 v[134:135], v[150:151], v[130:131] op_sel_hi:[0,1]
	v_pk_mul_f32 v[136:137], v[150:151], v[128:129] op_sel_hi:[0,1]
	global_load_dwordx4 v[128:131], v180, s[14:15] offset:144
	s_nop 0
	global_load_dwordx4 v[180:183], v180, s[14:15] offset:128
	s_or_b32 s14, s16, s29
	s_and_b64 s[6:7], s[6:7], exec
	s_cselect_b32 s6, 0x200, 0
	s_lshl_b32 s7, s14, 6
	s_or_b32 s6, s7, s6
	v_or_b32_e32 v224, s6, v148
	s_mov_b64 s[6:7], 0x40000
	s_waitcnt vmcnt(0)
	v_pk_mul_f32 v[184:185], v[150:151], v[182:183] op_sel_hi:[0,1]
	v_pk_mul_f32 v[182:183], v[150:151], v[128:129] op_sel_hi:[0,1]
	v_xor_b32_e32 v128, 16, v149
	v_cmp_lt_i32_e32 vcc, v128, v155
	v_pk_mul_f32 v[186:187], v[150:151], v[180:181] op_sel_hi:[0,1]
	v_pk_mul_f32 v[180:181], v[150:151], v[130:131] op_sel_hi:[0,1]
	v_cndmask_b32_e32 v128, v149, v128, vcc
	v_lshlrev_b32_e32 v213, 2, v128
	v_xor_b32_e32 v128, 32, v149
	v_cmp_lt_i32_e32 vcc, v128, v155
	v_pk_mul_f32 v[130:131], v[124:125], v[176:177] op_sel_hi:[1,0]
	s_nop 0
	v_cndmask_b32_e32 v128, v149, v128, vcc
	v_lshlrev_b32_e32 v212, 2, v128
	v_pk_mul_f32 v[128:129], v[126:127], v[176:177] op_sel_hi:[1,0]
	v_pk_mul_f32 v[190:191], v[130:131], v[130:131]
	v_pk_mul_f32 v[188:189], v[128:129], v[128:129]
	s_nop 0
	v_pk_mov_b32 v[192:193], v[190:191], v[188:189] op_sel:[1,0]
	v_mov_b32_e32 v191, v189
	v_pk_add_f32 v[188:189], v[192:193], v[190:191]
	v_pk_mul_f32 v[190:191], v[214:215], v[214:215]
	v_pk_mul_f32 v[192:193], v[216:217], v[216:217]
	v_pk_add_f32 v[188:189], v[188:189], v[188:189] op_sel_hi:[0,1]
	v_pk_mov_b32 v[194:195], v[192:193], v[190:191] op_sel:[1,0]
	v_mov_b32_e32 v193, v191
	v_pk_add_f32 v[190:191], v[194:195], v[192:193]
	v_pk_mul_f32 v[192:193], v[120:121], v[176:177] op_sel_hi:[1,0]
	v_pk_add_f32 v[218:219], v[190:191], v[190:191] op_sel_hi:[0,1]
	v_pk_mul_f32 v[190:191], v[122:123], v[176:177] op_sel_hi:[1,0]
	v_mul_f32_e32 v150, v192, v192
	v_pk_fma_f32 v[220:221], v[192:193], v[192:193], v[150:151] op_sel_hi:[1,1,0]
	v_mul_f32_e32 v150, v190, v190
	v_pk_fma_f32 v[222:223], v[190:191], v[190:191], v[150:151] op_sel_hi:[1,1,0]
	v_pk_mul_f32 v[194:195], v[114:115], v[176:177] op_sel_hi:[1,0]
	v_mul_f32_e32 v220, v196, v196
	v_mul_f32_e32 v222, v197, v197
	v_mul_f32_e32 v188, v194, v194
	v_mul_f32_e32 v218, v195, v195
	v_pk_add_f32 v[220:221], v[220:221], v[222:223]
	v_pk_add_f32 v[188:189], v[188:189], v[218:219]
	s_nop 0
	v_pk_add_f32 v[188:189], v[220:221], v[188:189]
	s_nop 0
	v_add_f32_e32 v150, v188, v189
	v_mov_b32_e32 v188, v150
	s_nop 1
	v_permlane16_swap_b32 v188, v150
	s_waitcnt lgkmcnt(0)
	v_add_f32_e32 v150, v150, v188
	v_mov_b32_e32 v188, v150
	s_nop 1
	v_permlane32_swap_b32 v188, v150
	s_waitcnt lgkmcnt(0)
	v_add_f32_e32 v150, v150, v188
	v_fmamk_f32 v150, v150, 0x3c800000, v206
	v_rsq_f32_e32 v198, v150
	v_lshlrev_b64 v[188:189], 11, v[174:175]
	v_lshl_add_u64 v[188:189], s[64:65], 0, v[188:189]
	v_lshlrev_b32_e32 v150, 1, v224
	v_pk_mul_f32 v[130:131], v[130:131], v[198:199] op_sel_hi:[1,0]
	v_pk_mul_f32 v[128:129], v[128:129], v[198:199] op_sel_hi:[1,0]
	v_pk_mul_f32 v[214:215], v[214:215], v[198:199] op_sel_hi:[1,0]
	v_pk_mul_f32 v[218:219], v[138:139], v[128:129]
	v_pk_mul_f32 v[128:129], v[178:179], v[130:131]
	v_pk_mul_f32 v[130:131], v[216:217], v[198:199] op_sel_hi:[1,0]
	v_cvt_pk_bf16_f32 v128, v128, v129
	v_cvt_pk_bf16_f32 v129, v218, v219
	v_lshl_add_u64 v[188:189], v[188:189], 0, v[150:151]
	v_pk_mul_f32 v[130:131], v[136:137], v[130:131]
	v_pk_mul_f32 v[214:215], v[134:135], v[214:215]
	v_cvt_pk_bf16_f32 v130, v130, v131
	s_nop 0
	v_cvt_pk_bf16_f32 v131, v214, v215
	global_store_dwordx4 v[188:189], v[128:131], off
	s_nop 1
	v_pk_mul_f32 v[128:129], v[192:193], v[198:199] op_sel_hi:[1,0]
	v_pk_mul_f32 v[130:131], v[190:191], v[198:199] op_sel_hi:[1,0]
	v_pk_mul_f32 v[128:129], v[186:187], v[128:129]
	v_pk_mul_f32 v[130:131], v[184:185], v[130:131]
	v_pk_mul_f32 v[190:191], v[196:197], v[198:199] op_sel_hi:[1,0]
	v_pk_mul_f32 v[192:193], v[194:195], v[198:199] op_sel_hi:[1,0]
	v_cvt_pk_bf16_f32 v128, v128, v129
	v_pk_mul_f32 v[190:191], v[182:183], v[190:191]
	v_pk_mul_f32 v[192:193], v[180:181], v[192:193]
	v_cvt_pk_bf16_f32 v129, v130, v131
	v_cvt_pk_bf16_f32 v130, v190, v191
	s_nop 0
	v_cvt_pk_bf16_f32 v131, v192, v193
	global_store_dwordx4 v[188:189], v[128:131], off offset:64
	s_nop 1
	v_mov_b32_e32 v128, v177
	v_pk_mul_f32 v[130:131], v[110:111], v[128:129] op_sel_hi:[1,0]
	v_pk_mul_f32 v[190:191], v[108:109], v[128:129] op_sel_hi:[1,0]
	v_pk_mul_f32 v[192:193], v[130:131], v[130:131]
	v_pk_mul_f32 v[194:195], v[190:191], v[190:191]
	v_pk_mul_f32 v[224:225], v[98:99], v[128:129] op_sel_hi:[1,0]
	v_pk_mov_b32 v[196:197], v[194:195], v[192:193] op_sel:[1,0]
	v_mov_b32_e32 v195, v193
	v_pk_add_f32 v[192:193], v[196:197], v[194:195]
	v_pk_mul_f32 v[194:195], v[102:103], v[128:129] op_sel_hi:[1,0]
	v_pk_mul_f32 v[196:197], v[100:101], v[128:129] op_sel_hi:[1,0]
	v_pk_mul_f32 v[214:215], v[194:195], v[194:195]
	v_pk_mul_f32 v[216:217], v[196:197], v[196:197]
	v_pk_add_f32 v[192:193], v[192:193], v[192:193] op_sel_hi:[0,1]
	v_pk_mov_b32 v[218:219], v[216:217], v[214:215] op_sel:[1,0]
	v_mov_b32_e32 v217, v215
	v_pk_add_f32 v[214:215], v[218:219], v[216:217]
	v_pk_mul_f32 v[218:219], v[104:105], v[128:129] op_sel_hi:[1,0]
	v_pk_mul_f32 v[216:217], v[106:107], v[128:129] op_sel_hi:[1,0]
	v_mul_f32_e32 v192, v218, v218
	v_pk_fma_f32 v[220:221], v[218:219], v[218:219], v[192:193] op_sel_hi:[1,1,0]
	v_mul_f32_e32 v192, v216, v216
	v_pk_add_f32 v[214:215], v[214:215], v[214:215] op_sel_hi:[0,1]
	v_pk_fma_f32 v[222:223], v[216:217], v[216:217], v[192:193] op_sel_hi:[1,1,0]
	v_pk_mul_f32 v[226:227], v[96:97], v[128:129] op_sel_hi:[1,0]
	v_mul_f32_e32 v192, v224, v224
	v_mul_f32_e32 v220, v226, v226
	v_mul_f32_e32 v222, v227, v227
	v_mul_f32_e32 v214, v225, v225
	v_pk_add_f32 v[128:129], v[220:221], v[222:223]
	v_pk_add_f32 v[192:193], v[192:193], v[214:215]
	v_lshlrev_b64 v[214:215], 11, v[170:171]
	v_pk_add_f32 v[128:129], v[128:129], v[192:193]
	v_pk_mul_f32 v[222:223], v[82:83], v[172:173] op_sel_hi:[1,0]
	v_add_f32_e32 v128, v128, v129
	v_mov_b32_e32 v129, v128
	s_nop 1
	v_permlane16_swap_b32 v129, v128
	s_waitcnt lgkmcnt(0)
	v_add_f32_e32 v128, v128, v129
	v_mov_b32_e32 v129, v128
	s_nop 1
	v_permlane32_swap_b32 v129, v128
	s_waitcnt lgkmcnt(0)
	v_add_f32_e32 v128, v128, v129
	v_fmamk_f32 v128, v128, 0x3c800000, v206
	v_rsq_f32_e32 v192, v128
	s_nop 0
	v_pk_mul_f32 v[128:129], v[190:191], v[192:193] op_sel_hi:[1,0]
	v_pk_mul_f32 v[130:131], v[130:131], v[192:193] op_sel_hi:[1,0]
	v_pk_mul_f32 v[190:191], v[196:197], v[192:193] op_sel_hi:[1,0]
	v_pk_mul_f32 v[130:131], v[138:139], v[130:131]
	v_pk_mul_f32 v[128:129], v[178:179], v[128:129]
	v_pk_mul_f32 v[190:191], v[136:137], v[190:191]
	v_pk_mul_f32 v[194:195], v[194:195], v[192:193] op_sel_hi:[1,0]
	v_cvt_pk_bf16_f32 v128, v128, v129
	v_cvt_pk_bf16_f32 v129, v130, v131
	v_cvt_pk_bf16_f32 v130, v190, v191
	v_lshl_add_u64 v[190:191], s[64:65], 0, v[214:215]
	v_pk_mul_f32 v[194:195], v[134:135], v[194:195]
	v_lshl_add_u64 v[190:191], v[190:191], 0, v[150:151]
	v_cvt_pk_bf16_f32 v131, v194, v195
	global_store_dwordx4 v[190:191], v[128:131], off
	v_pk_mul_f32 v[194:195], v[226:227], v[192:193] op_sel_hi:[1,0]
	s_nop 0
	v_pk_mul_f32 v[128:129], v[218:219], v[192:193] op_sel_hi:[1,0]
	v_pk_mul_f32 v[130:131], v[216:217], v[192:193] op_sel_hi:[1,0]
	v_pk_mul_f32 v[128:129], v[186:187], v[128:129]
	v_pk_mul_f32 v[130:131], v[184:185], v[130:131]
	v_pk_mul_f32 v[192:193], v[224:225], v[192:193] op_sel_hi:[1,0]
	v_pk_mul_f32 v[194:195], v[182:183], v[194:195]
	v_pk_mul_f32 v[192:193], v[180:181], v[192:193]
	v_cvt_pk_bf16_f32 v128, v128, v129
	v_cvt_pk_bf16_f32 v129, v130, v131
	v_cvt_pk_bf16_f32 v130, v194, v195
	v_pk_mul_f32 v[224:225], v[80:81], v[172:173] op_sel_hi:[1,0]
	v_cvt_pk_bf16_f32 v131, v192, v193
	global_store_dwordx4 v[190:191], v[128:131], off offset:64
	s_nop 1
	v_pk_mul_f32 v[128:129], v[94:95], v[172:173] op_sel_hi:[1,0]
	v_pk_mul_f32 v[130:131], v[92:93], v[172:173] op_sel_hi:[1,0]
	v_pk_mul_f32 v[190:191], v[128:129], v[128:129]
	v_pk_mul_f32 v[192:193], v[130:131], v[130:131]
	s_nop 0
	v_pk_mov_b32 v[194:195], v[192:193], v[190:191] op_sel:[1,0]
	v_mov_b32_e32 v193, v191
	v_pk_add_f32 v[190:191], v[194:195], v[192:193]
	v_pk_mul_f32 v[192:193], v[86:87], v[172:173] op_sel_hi:[1,0]
	v_pk_mul_f32 v[194:195], v[84:85], v[172:173] op_sel_hi:[1,0]
	v_pk_mul_f32 v[196:197], v[192:193], v[192:193]
	v_pk_mul_f32 v[214:215], v[194:195], v[194:195]
	v_pk_add_f32 v[190:191], v[190:191], v[190:191] op_sel_hi:[0,1]
	v_pk_mov_b32 v[216:217], v[214:215], v[196:197] op_sel:[1,0]
	v_mov_b32_e32 v215, v197
	v_pk_add_f32 v[196:197], v[216:217], v[214:215]
	v_pk_mul_f32 v[216:217], v[88:89], v[172:173] op_sel_hi:[1,0]
	v_pk_mul_f32 v[214:215], v[90:91], v[172:173] op_sel_hi:[1,0]
	v_mul_f32_e32 v190, v216, v216
	v_pk_fma_f32 v[218:219], v[216:217], v[216:217], v[190:191] op_sel_hi:[1,1,0]
	v_mul_f32_e32 v190, v214, v214
	v_pk_add_f32 v[196:197], v[196:197], v[196:197] op_sel_hi:[0,1]
	v_pk_fma_f32 v[220:221], v[214:215], v[214:215], v[190:191] op_sel_hi:[1,1,0]
	v_mul_f32_e32 v218, v224, v224
	v_mul_f32_e32 v220, v225, v225
	v_mul_f32_e32 v190, v222, v222
	v_mul_f32_e32 v196, v223, v223
	v_pk_add_f32 v[218:219], v[218:219], v[220:221]
	v_pk_add_f32 v[190:191], v[190:191], v[196:197]
	v_lshlrev_b64 v[196:197], 11, v[166:167]
	v_pk_add_f32 v[190:191], v[218:219], v[190:191]
	s_nop 0
	v_add_f32_e32 v190, v190, v191
	v_mov_b32_e32 v191, v190
	s_nop 1
	v_permlane16_swap_b32 v191, v190
	s_waitcnt lgkmcnt(0)
	v_add_f32_e32 v190, v190, v191
	v_mov_b32_e32 v191, v190
	s_nop 1
	v_permlane32_swap_b32 v191, v190
	s_waitcnt lgkmcnt(0)
	v_add_f32_e32 v190, v190, v191
	v_fmamk_f32 v190, v190, 0x3c800000, v206
	v_rsq_f32_e32 v190, v190
	s_nop 0
	v_pk_mul_f32 v[130:131], v[130:131], v[190:191] op_sel_hi:[1,0]
	v_pk_mul_f32 v[128:129], v[128:129], v[190:191] op_sel_hi:[1,0]
	v_pk_mul_f32 v[192:193], v[192:193], v[190:191] op_sel_hi:[1,0]
	v_pk_mul_f32 v[218:219], v[138:139], v[128:129]
	v_pk_mul_f32 v[128:129], v[178:179], v[130:131]
	v_pk_mul_f32 v[130:131], v[194:195], v[190:191] op_sel_hi:[1,0]
	v_pk_mul_f32 v[192:193], v[134:135], v[192:193]
	v_pk_mul_f32 v[130:131], v[136:137], v[130:131]
	v_cvt_pk_bf16_f32 v128, v128, v129
	v_cvt_pk_bf16_f32 v129, v218, v219
	v_pk_mul_f32 v[194:195], v[224:225], v[190:191] op_sel_hi:[1,0]
	v_cvt_pk_bf16_f32 v130, v130, v131
	v_cvt_pk_bf16_f32 v131, v192, v193
	v_lshl_add_u64 v[192:193], s[64:65], 0, v[196:197]
	v_lshl_add_u64 v[192:193], v[192:193], 0, v[150:151]
	global_store_dwordx4 v[192:193], v[128:131], off
	v_pk_mul_f32 v[194:195], v[182:183], v[194:195]
	s_nop 0
	v_pk_mul_f32 v[128:129], v[216:217], v[190:191] op_sel_hi:[1,0]
	v_pk_mul_f32 v[130:131], v[214:215], v[190:191] op_sel_hi:[1,0]
	v_pk_mul_f32 v[128:129], v[186:187], v[128:129]
	v_pk_mul_f32 v[130:131], v[184:185], v[130:131]
	v_pk_mul_f32 v[190:191], v[222:223], v[190:191] op_sel_hi:[1,0]
	v_cvt_pk_bf16_f32 v128, v128, v129
	v_cvt_pk_bf16_f32 v129, v130, v131
	v_cvt_pk_bf16_f32 v130, v194, v195
	s_nop 0
	v_pk_mul_f32 v[190:191], v[180:181], v[190:191]
	s_nop 0
	v_cvt_pk_bf16_f32 v131, v190, v191
	global_store_dwordx4 v[192:193], v[128:131], off offset:64
	s_nop 1
	v_mov_b32_e32 v128, v173
	v_pk_mul_f32 v[130:131], v[78:79], v[128:129] op_sel_hi:[1,0]
	v_pk_mul_f32 v[190:191], v[76:77], v[128:129] op_sel_hi:[1,0]
	v_pk_mul_f32 v[192:193], v[130:131], v[130:131]
	v_pk_mul_f32 v[194:195], v[190:191], v[190:191]
	v_pk_mul_f32 v[224:225], v[66:67], v[128:129] op_sel_hi:[1,0]
	v_pk_mov_b32 v[196:197], v[194:195], v[192:193] op_sel:[1,0]
	v_mov_b32_e32 v195, v193
	v_pk_add_f32 v[192:193], v[196:197], v[194:195]
	v_pk_mul_f32 v[194:195], v[70:71], v[128:129] op_sel_hi:[1,0]
	v_pk_mul_f32 v[196:197], v[68:69], v[128:129] op_sel_hi:[1,0]
	v_pk_mul_f32 v[214:215], v[194:195], v[194:195]
	v_pk_mul_f32 v[216:217], v[196:197], v[196:197]
	v_pk_add_f32 v[192:193], v[192:193], v[192:193] op_sel_hi:[0,1]
	v_pk_mov_b32 v[218:219], v[216:217], v[214:215] op_sel:[1,0]
	v_mov_b32_e32 v217, v215
	v_pk_add_f32 v[214:215], v[218:219], v[216:217]
	v_pk_mul_f32 v[218:219], v[72:73], v[128:129] op_sel_hi:[1,0]
	v_pk_mul_f32 v[216:217], v[74:75], v[128:129] op_sel_hi:[1,0]
	v_mul_f32_e32 v192, v218, v218
	v_pk_fma_f32 v[220:221], v[218:219], v[218:219], v[192:193] op_sel_hi:[1,1,0]
	v_mul_f32_e32 v192, v216, v216
	v_pk_add_f32 v[214:215], v[214:215], v[214:215] op_sel_hi:[0,1]
	v_pk_fma_f32 v[222:223], v[216:217], v[216:217], v[192:193] op_sel_hi:[1,1,0]
	v_pk_mul_f32 v[226:227], v[64:65], v[128:129] op_sel_hi:[1,0]
	v_mul_f32_e32 v192, v224, v224
	v_mul_f32_e32 v220, v226, v226
	v_mul_f32_e32 v222, v227, v227
	v_mul_f32_e32 v214, v225, v225
	v_pk_add_f32 v[128:129], v[220:221], v[222:223]
	v_pk_add_f32 v[192:193], v[192:193], v[214:215]
	v_lshlrev_b64 v[214:215], 11, v[164:165]
	v_pk_add_f32 v[128:129], v[128:129], v[192:193]
	v_pk_mul_f32 v[222:223], v[50:51], v[168:169] op_sel_hi:[1,0]
	v_add_f32_e32 v128, v128, v129
	v_mov_b32_e32 v129, v128
	s_nop 1
	v_permlane16_swap_b32 v129, v128
	s_waitcnt lgkmcnt(0)
	v_add_f32_e32 v128, v128, v129
	v_mov_b32_e32 v129, v128
	s_nop 1
	v_permlane32_swap_b32 v129, v128
	s_waitcnt lgkmcnt(0)
	v_add_f32_e32 v128, v128, v129
	v_fmamk_f32 v128, v128, 0x3c800000, v206
	v_rsq_f32_e32 v192, v128
	s_nop 0
	v_pk_mul_f32 v[128:129], v[190:191], v[192:193] op_sel_hi:[1,0]
	v_pk_mul_f32 v[130:131], v[130:131], v[192:193] op_sel_hi:[1,0]
	v_pk_mul_f32 v[190:191], v[196:197], v[192:193] op_sel_hi:[1,0]
	v_pk_mul_f32 v[130:131], v[138:139], v[130:131]
	v_pk_mul_f32 v[128:129], v[178:179], v[128:129]
	v_pk_mul_f32 v[190:191], v[136:137], v[190:191]
	v_pk_mul_f32 v[194:195], v[194:195], v[192:193] op_sel_hi:[1,0]
	v_cvt_pk_bf16_f32 v128, v128, v129
	v_cvt_pk_bf16_f32 v129, v130, v131
	v_cvt_pk_bf16_f32 v130, v190, v191
	v_lshl_add_u64 v[190:191], s[64:65], 0, v[214:215]
	v_pk_mul_f32 v[194:195], v[134:135], v[194:195]
	v_lshl_add_u64 v[190:191], v[190:191], 0, v[150:151]
	v_cvt_pk_bf16_f32 v131, v194, v195
	global_store_dwordx4 v[190:191], v[128:131], off
	v_pk_mul_f32 v[194:195], v[226:227], v[192:193] op_sel_hi:[1,0]
	s_nop 0
	v_pk_mul_f32 v[128:129], v[218:219], v[192:193] op_sel_hi:[1,0]
	v_pk_mul_f32 v[130:131], v[216:217], v[192:193] op_sel_hi:[1,0]
	v_pk_mul_f32 v[128:129], v[186:187], v[128:129]
	v_pk_mul_f32 v[130:131], v[184:185], v[130:131]
	v_pk_mul_f32 v[192:193], v[224:225], v[192:193] op_sel_hi:[1,0]
	v_pk_mul_f32 v[194:195], v[182:183], v[194:195]
	v_pk_mul_f32 v[192:193], v[180:181], v[192:193]
	v_cvt_pk_bf16_f32 v128, v128, v129
	v_cvt_pk_bf16_f32 v129, v130, v131
	v_cvt_pk_bf16_f32 v130, v194, v195
	v_pk_mul_f32 v[224:225], v[48:49], v[168:169] op_sel_hi:[1,0]
	v_cvt_pk_bf16_f32 v131, v192, v193
	global_store_dwordx4 v[190:191], v[128:131], off offset:64
	s_nop 1
	v_pk_mul_f32 v[128:129], v[62:63], v[168:169] op_sel_hi:[1,0]
	v_pk_mul_f32 v[130:131], v[60:61], v[168:169] op_sel_hi:[1,0]
	v_pk_mul_f32 v[190:191], v[128:129], v[128:129]
	v_pk_mul_f32 v[192:193], v[130:131], v[130:131]
	s_nop 0
	v_pk_mov_b32 v[194:195], v[192:193], v[190:191] op_sel:[1,0]
	v_mov_b32_e32 v193, v191
	v_pk_add_f32 v[190:191], v[194:195], v[192:193]
	v_pk_mul_f32 v[192:193], v[54:55], v[168:169] op_sel_hi:[1,0]
	v_pk_mul_f32 v[194:195], v[52:53], v[168:169] op_sel_hi:[1,0]
	v_pk_mul_f32 v[196:197], v[192:193], v[192:193]
	v_pk_mul_f32 v[214:215], v[194:195], v[194:195]
	v_pk_add_f32 v[190:191], v[190:191], v[190:191] op_sel_hi:[0,1]
	v_pk_mov_b32 v[216:217], v[214:215], v[196:197] op_sel:[1,0]
	v_mov_b32_e32 v215, v197
	v_pk_add_f32 v[196:197], v[216:217], v[214:215]
	v_pk_mul_f32 v[216:217], v[56:57], v[168:169] op_sel_hi:[1,0]
	v_pk_mul_f32 v[214:215], v[58:59], v[168:169] op_sel_hi:[1,0]
	v_mul_f32_e32 v150, v216, v216
	v_pk_fma_f32 v[218:219], v[216:217], v[216:217], v[150:151] op_sel_hi:[1,1,0]
	v_mul_f32_e32 v150, v214, v214
	v_pk_add_f32 v[196:197], v[196:197], v[196:197] op_sel_hi:[0,1]
	v_pk_fma_f32 v[220:221], v[214:215], v[214:215], v[150:151] op_sel_hi:[1,1,0]
	v_mul_f32_e32 v218, v224, v224
	v_mul_f32_e32 v220, v225, v225
	v_mul_f32_e32 v190, v222, v222
	v_mul_f32_e32 v196, v223, v223
	v_pk_add_f32 v[218:219], v[218:219], v[220:221]
	v_pk_add_f32 v[190:191], v[190:191], v[196:197]
	s_nop 0
	v_pk_add_f32 v[190:191], v[218:219], v[190:191]
	s_nop 0
	v_add_f32_e32 v150, v190, v191
	v_mov_b32_e32 v190, v150
	s_nop 1
	v_permlane16_swap_b32 v190, v150
	s_waitcnt lgkmcnt(0)
	v_add_f32_e32 v150, v150, v190
	v_mov_b32_e32 v190, v150
	s_nop 1
	v_permlane32_swap_b32 v190, v150
	s_waitcnt lgkmcnt(0)
	v_add_f32_e32 v150, v150, v190
	v_fmamk_f32 v150, v150, 0x3c800000, v206
	v_rsq_f32_e32 v150, v150
	s_nop 0
	v_pk_mul_f32 v[130:131], v[130:131], v[150:151] op_sel_hi:[1,0]
	v_pk_mul_f32 v[128:129], v[128:129], v[150:151] op_sel_hi:[1,0]
	v_pk_mul_f32 v[192:193], v[192:193], v[150:151] op_sel_hi:[1,0]
	v_pk_mul_f32 v[190:191], v[138:139], v[128:129]
	v_pk_mul_f32 v[128:129], v[178:179], v[130:131]
	v_pk_mul_f32 v[130:131], v[194:195], v[150:151] op_sel_hi:[1,0]
	v_pk_mul_f32 v[192:193], v[134:135], v[192:193]
	v_pk_mul_f32 v[130:131], v[136:137], v[130:131]
	v_cvt_pk_bf16_f32 v128, v128, v129
	v_cvt_pk_bf16_f32 v129, v190, v191
	v_lshl_add_u64 v[190:191], v[188:189], 0, s[6:7]
	v_cvt_pk_bf16_f32 v130, v130, v131
	v_cvt_pk_bf16_f32 v131, v192, v193
	v_add_co_u32_e32 v192, vcc, s36, v188
	v_pk_mul_f32 v[194:195], v[222:223], v[150:151] op_sel_hi:[1,0]
	s_nop 0
	v_addc_co_u32_e32 v193, vcc, 0, v189, vcc
	global_store_dwordx4 v[192:193], v[128:131], off
	v_pk_mul_f32 v[192:193], v[224:225], v[150:151] op_sel_hi:[1,0]
	v_pk_mul_f32 v[194:195], v[180:181], v[194:195]
	v_pk_mul_f32 v[128:129], v[216:217], v[150:151] op_sel_hi:[1,0]
	v_pk_mul_f32 v[130:131], v[214:215], v[150:151] op_sel_hi:[1,0]
	v_pk_mul_f32 v[128:129], v[186:187], v[128:129]
	v_pk_mul_f32 v[130:131], v[184:185], v[130:131]
	v_cvt_pk_bf16_f32 v128, v128, v129
	v_pk_mul_f32 v[192:193], v[182:183], v[192:193]
	v_cvt_pk_bf16_f32 v129, v130, v131
	s_mov_b64 s[6:7], 0x48000
	v_cvt_pk_bf16_f32 v130, v192, v193
	v_cvt_pk_bf16_f32 v131, v194, v195
	global_store_dwordx4 v[190:191], v[128:131], off offset:64
	s_nop 1
	v_mov_b32_e32 v128, v169
	v_pk_mul_f32 v[130:131], v[46:47], v[128:129] op_sel_hi:[1,0]
	v_pk_mul_f32 v[190:191], v[44:45], v[128:129] op_sel_hi:[1,0]
	v_pk_mul_f32 v[192:193], v[130:131], v[130:131]
	v_pk_mul_f32 v[194:195], v[190:191], v[190:191]
	v_pk_mul_f32 v[224:225], v[34:35], v[128:129] op_sel_hi:[1,0]
	v_pk_mov_b32 v[196:197], v[194:195], v[192:193] op_sel:[1,0]
	v_mov_b32_e32 v195, v193
	v_pk_add_f32 v[192:193], v[196:197], v[194:195]
	v_pk_mul_f32 v[194:195], v[38:39], v[128:129] op_sel_hi:[1,0]
	v_pk_mul_f32 v[196:197], v[36:37], v[128:129] op_sel_hi:[1,0]
	v_pk_mul_f32 v[214:215], v[194:195], v[194:195]
	v_pk_mul_f32 v[216:217], v[196:197], v[196:197]
	v_pk_add_f32 v[192:193], v[192:193], v[192:193] op_sel_hi:[0,1]
	v_pk_mov_b32 v[218:219], v[216:217], v[214:215] op_sel:[1,0]
	v_mov_b32_e32 v217, v215
	v_pk_add_f32 v[214:215], v[218:219], v[216:217]
	v_pk_mul_f32 v[218:219], v[40:41], v[128:129] op_sel_hi:[1,0]
	v_pk_mul_f32 v[216:217], v[42:43], v[128:129] op_sel_hi:[1,0]
	v_mul_f32_e32 v150, v218, v218
	v_pk_fma_f32 v[220:221], v[218:219], v[218:219], v[150:151] op_sel_hi:[1,1,0]
	v_mul_f32_e32 v150, v216, v216
	v_pk_add_f32 v[214:215], v[214:215], v[214:215] op_sel_hi:[0,1]
	v_pk_fma_f32 v[222:223], v[216:217], v[216:217], v[150:151] op_sel_hi:[1,1,0]
	v_pk_mul_f32 v[226:227], v[32:33], v[128:129] op_sel_hi:[1,0]
	v_mul_f32_e32 v192, v224, v224
	v_mul_f32_e32 v220, v226, v226
	v_mul_f32_e32 v222, v227, v227
	v_mul_f32_e32 v214, v225, v225
	v_pk_add_f32 v[128:129], v[220:221], v[222:223]
	v_pk_add_f32 v[192:193], v[192:193], v[214:215]
	v_pk_mul_f32 v[222:223], v[18:19], v[132:133] op_sel_hi:[1,0]
	v_pk_add_f32 v[128:129], v[128:129], v[192:193]
	s_nop 0
	v_add_f32_e32 v128, v128, v129
	v_mov_b32_e32 v129, v128
	s_nop 1
	v_permlane16_swap_b32 v129, v128
	s_waitcnt lgkmcnt(0)
	v_add_f32_e32 v128, v128, v129
	v_mov_b32_e32 v129, v128
	s_nop 1
	v_permlane32_swap_b32 v129, v128
	s_waitcnt lgkmcnt(0)
	v_add_f32_e32 v128, v128, v129
	v_fmamk_f32 v128, v128, 0x3c800000, v206
	v_rsq_f32_e32 v150, v128
	s_nop 0
	v_pk_mul_f32 v[128:129], v[190:191], v[150:151] op_sel_hi:[1,0]
	v_pk_mul_f32 v[130:131], v[130:131], v[150:151] op_sel_hi:[1,0]
	v_pk_mul_f32 v[192:193], v[194:195], v[150:151] op_sel_hi:[1,0]
	v_pk_mul_f32 v[130:131], v[138:139], v[130:131]
	v_pk_mul_f32 v[128:129], v[178:179], v[128:129]
	v_pk_mul_f32 v[190:191], v[196:197], v[150:151] op_sel_hi:[1,0]
	v_pk_mul_f32 v[192:193], v[134:135], v[192:193]
	v_pk_mul_f32 v[190:191], v[136:137], v[190:191]
	v_cvt_pk_bf16_f32 v128, v128, v129
	v_cvt_pk_bf16_f32 v129, v130, v131
	v_pk_mul_f32 v[194:195], v[224:225], v[150:151] op_sel_hi:[1,0]
	v_cvt_pk_bf16_f32 v130, v190, v191
	v_cvt_pk_bf16_f32 v131, v192, v193
	v_add_co_u32_e32 v192, vcc, s37, v188
	v_lshl_add_u64 v[190:191], v[188:189], 0, s[6:7]
	s_nop 0
	v_addc_co_u32_e32 v193, vcc, 0, v189, vcc
	global_store_dwordx4 v[192:193], v[128:131], off
	v_pk_mul_f32 v[192:193], v[226:227], v[150:151] op_sel_hi:[1,0]
	v_pk_mul_f32 v[194:195], v[180:181], v[194:195]
	v_pk_mul_f32 v[128:129], v[218:219], v[150:151] op_sel_hi:[1,0]
	v_pk_mul_f32 v[130:131], v[216:217], v[150:151] op_sel_hi:[1,0]
	v_pk_mul_f32 v[128:129], v[186:187], v[128:129]
	v_pk_mul_f32 v[130:131], v[184:185], v[130:131]
	v_pk_mul_f32 v[192:193], v[182:183], v[192:193]
	v_cvt_pk_bf16_f32 v128, v128, v129
	v_cvt_pk_bf16_f32 v129, v130, v131
	v_pk_mul_f32 v[224:225], v[16:17], v[132:133] op_sel_hi:[1,0]
	v_cvt_pk_bf16_f32 v130, v192, v193
	v_cvt_pk_bf16_f32 v131, v194, v195
	global_store_dwordx4 v[190:191], v[128:131], off offset:64
	s_mov_b64 s[6:7], 0x50000
	s_nop 0
	v_pk_mul_f32 v[128:129], v[30:31], v[132:133] op_sel_hi:[1,0]
	v_pk_mul_f32 v[130:131], v[28:29], v[132:133] op_sel_hi:[1,0]
	v_pk_mul_f32 v[190:191], v[128:129], v[128:129]
	v_pk_mul_f32 v[192:193], v[130:131], v[130:131]
	s_nop 0
	v_pk_mov_b32 v[194:195], v[192:193], v[190:191] op_sel:[1,0]
	v_mov_b32_e32 v193, v191
	v_pk_add_f32 v[190:191], v[194:195], v[192:193]
	v_pk_mul_f32 v[192:193], v[22:23], v[132:133] op_sel_hi:[1,0]
	v_pk_mul_f32 v[194:195], v[20:21], v[132:133] op_sel_hi:[1,0]
	v_pk_mul_f32 v[196:197], v[192:193], v[192:193]
	v_pk_mul_f32 v[214:215], v[194:195], v[194:195]
	v_pk_add_f32 v[190:191], v[190:191], v[190:191] op_sel_hi:[0,1]
	v_pk_mov_b32 v[216:217], v[214:215], v[196:197] op_sel:[1,0]
	v_mov_b32_e32 v215, v197
	v_pk_add_f32 v[196:197], v[216:217], v[214:215]
	v_pk_mul_f32 v[216:217], v[24:25], v[132:133] op_sel_hi:[1,0]
	v_pk_mul_f32 v[214:215], v[26:27], v[132:133] op_sel_hi:[1,0]
	v_mul_f32_e32 v150, v216, v216
	v_pk_fma_f32 v[218:219], v[216:217], v[216:217], v[150:151] op_sel_hi:[1,1,0]
	v_mul_f32_e32 v150, v214, v214
	v_pk_add_f32 v[196:197], v[196:197], v[196:197] op_sel_hi:[0,1]
	v_pk_fma_f32 v[220:221], v[214:215], v[214:215], v[150:151] op_sel_hi:[1,1,0]
	v_mul_f32_e32 v218, v224, v224
	v_mul_f32_e32 v220, v225, v225
	v_mul_f32_e32 v190, v222, v222
	v_mul_f32_e32 v196, v223, v223
	v_pk_add_f32 v[218:219], v[218:219], v[220:221]
	v_pk_add_f32 v[190:191], v[190:191], v[196:197]
	s_nop 0
	v_pk_add_f32 v[190:191], v[218:219], v[190:191]
	s_nop 0
	v_add_f32_e32 v150, v190, v191
	v_mov_b32_e32 v190, v150
	s_nop 1
	v_permlane16_swap_b32 v190, v150
	s_waitcnt lgkmcnt(0)
	v_add_f32_e32 v150, v150, v190
	v_mov_b32_e32 v190, v150
	s_nop 1
	v_permlane32_swap_b32 v190, v150
	s_waitcnt lgkmcnt(0)
	v_add_f32_e32 v150, v150, v190
	v_fmamk_f32 v150, v150, 0x3c800000, v206
	v_rsq_f32_e32 v150, v150
	s_nop 0
	v_pk_mul_f32 v[130:131], v[130:131], v[150:151] op_sel_hi:[1,0]
	v_pk_mul_f32 v[128:129], v[128:129], v[150:151] op_sel_hi:[1,0]
	v_pk_mul_f32 v[192:193], v[192:193], v[150:151] op_sel_hi:[1,0]
	v_pk_mul_f32 v[190:191], v[138:139], v[128:129]
	v_pk_mul_f32 v[128:129], v[178:179], v[130:131]
	v_pk_mul_f32 v[130:131], v[194:195], v[150:151] op_sel_hi:[1,0]
	v_pk_mul_f32 v[192:193], v[134:135], v[192:193]
	v_pk_mul_f32 v[130:131], v[136:137], v[130:131]
	v_cvt_pk_bf16_f32 v128, v128, v129
	v_cvt_pk_bf16_f32 v129, v190, v191
	v_lshl_add_u64 v[190:191], v[188:189], 0, s[6:7]
	v_cvt_pk_bf16_f32 v130, v130, v131
	v_cvt_pk_bf16_f32 v131, v192, v193
	v_add_co_u32_e32 v192, vcc, s38, v188
	v_pk_mul_f32 v[194:195], v[222:223], v[150:151] op_sel_hi:[1,0]
	s_nop 0
	v_addc_co_u32_e32 v193, vcc, 0, v189, vcc
	global_store_dwordx4 v[192:193], v[128:131], off
	v_pk_mul_f32 v[192:193], v[224:225], v[150:151] op_sel_hi:[1,0]
	v_pk_mul_f32 v[194:195], v[180:181], v[194:195]
	v_pk_mul_f32 v[128:129], v[216:217], v[150:151] op_sel_hi:[1,0]
	v_pk_mul_f32 v[130:131], v[214:215], v[150:151] op_sel_hi:[1,0]
	v_pk_mul_f32 v[128:129], v[186:187], v[128:129]
	v_pk_mul_f32 v[130:131], v[184:185], v[130:131]
	v_cvt_pk_bf16_f32 v128, v128, v129
	v_pk_mul_f32 v[192:193], v[182:183], v[192:193]
	v_cvt_pk_bf16_f32 v129, v130, v131
	s_mov_b64 s[6:7], 0x58000
	v_cvt_pk_bf16_f32 v130, v192, v193
	v_cvt_pk_bf16_f32 v131, v194, v195
	global_store_dwordx4 v[190:191], v[128:131], off offset:64
	s_nop 1
	v_mov_b32_e32 v128, v133
	v_pk_mul_f32 v[130:131], v[14:15], v[128:129] op_sel_hi:[1,0]
	v_pk_mul_f32 v[190:191], v[12:13], v[128:129] op_sel_hi:[1,0]
	v_pk_mul_f32 v[192:193], v[130:131], v[130:131]
	v_pk_mul_f32 v[194:195], v[190:191], v[190:191]
	v_pk_mul_f32 v[224:225], v[2:3], v[128:129] op_sel_hi:[1,0]
	v_pk_mov_b32 v[196:197], v[194:195], v[192:193] op_sel:[1,0]
	v_mov_b32_e32 v195, v193
	v_pk_add_f32 v[192:193], v[196:197], v[194:195]
	v_pk_mul_f32 v[194:195], v[6:7], v[128:129] op_sel_hi:[1,0]
	v_pk_mul_f32 v[196:197], v[4:5], v[128:129] op_sel_hi:[1,0]
	v_pk_mul_f32 v[214:215], v[194:195], v[194:195]
	v_pk_mul_f32 v[216:217], v[196:197], v[196:197]
	v_pk_add_f32 v[192:193], v[192:193], v[192:193] op_sel_hi:[0,1]
	v_pk_mov_b32 v[218:219], v[216:217], v[214:215] op_sel:[1,0]
	v_mov_b32_e32 v217, v215
	v_pk_add_f32 v[214:215], v[218:219], v[216:217]
	v_pk_mul_f32 v[218:219], v[8:9], v[128:129] op_sel_hi:[1,0]
	v_pk_mul_f32 v[216:217], v[10:11], v[128:129] op_sel_hi:[1,0]
	v_mul_f32_e32 v150, v218, v218
	v_pk_fma_f32 v[220:221], v[218:219], v[218:219], v[150:151] op_sel_hi:[1,1,0]
	v_mul_f32_e32 v150, v216, v216
	v_pk_add_f32 v[214:215], v[214:215], v[214:215] op_sel_hi:[0,1]
	v_pk_fma_f32 v[222:223], v[216:217], v[216:217], v[150:151] op_sel_hi:[1,1,0]
	v_pk_mul_f32 v[226:227], v[0:1], v[128:129] op_sel_hi:[1,0]
	v_mul_f32_e32 v192, v224, v224
	v_mul_f32_e32 v220, v226, v226
	v_mul_f32_e32 v222, v227, v227
	v_mul_f32_e32 v214, v225, v225
	v_pk_add_f32 v[128:129], v[220:221], v[222:223]
	v_pk_add_f32 v[192:193], v[192:193], v[214:215]
	s_nop 0
	v_pk_add_f32 v[128:129], v[128:129], v[192:193]
	s_nop 0
	v_add_f32_e32 v128, v128, v129
	v_mov_b32_e32 v129, v128
	s_nop 1
	v_permlane16_swap_b32 v129, v128
	s_waitcnt lgkmcnt(0)
	v_add_f32_e32 v128, v128, v129
	v_mov_b32_e32 v129, v128
	s_nop 1
	v_permlane32_swap_b32 v129, v128
	s_waitcnt lgkmcnt(0)
	v_add_f32_e32 v128, v128, v129
	v_fmamk_f32 v128, v128, 0x3c800000, v206
	v_rsq_f32_e32 v150, v128
	s_nop 0
	v_pk_mul_f32 v[128:129], v[190:191], v[150:151] op_sel_hi:[1,0]
	v_pk_mul_f32 v[130:131], v[130:131], v[150:151] op_sel_hi:[1,0]
	v_pk_mul_f32 v[128:129], v[178:179], v[128:129]
	v_pk_mul_f32 v[178:179], v[194:195], v[150:151] op_sel_hi:[1,0]
	v_pk_mul_f32 v[130:131], v[138:139], v[130:131]
	v_pk_mul_f32 v[138:139], v[196:197], v[150:151] op_sel_hi:[1,0]
	v_pk_mul_f32 v[134:135], v[134:135], v[178:179]
	v_pk_mul_f32 v[136:137], v[136:137], v[138:139]
	v_cvt_pk_bf16_f32 v128, v128, v129
	v_cvt_pk_bf16_f32 v129, v130, v131
	v_pk_mul_f32 v[138:139], v[224:225], v[150:151] op_sel_hi:[1,0]
	v_cvt_pk_bf16_f32 v130, v136, v137
	v_cvt_pk_bf16_f32 v131, v134, v135
	v_lshl_add_u64 v[134:135], v[188:189], 0, s[6:7]
	s_mov_b32 s6, 0x58000
	v_add_co_u32_e32 v136, vcc, s6, v188
	v_pk_mul_f32 v[138:139], v[180:181], v[138:139]
	s_nop 0
	v_addc_co_u32_e32 v137, vcc, 0, v189, vcc
	global_store_dwordx4 v[136:137], v[128:131], off
	v_pk_mul_f32 v[136:137], v[226:227], v[150:151] op_sel_hi:[1,0]
	s_nop 0
	v_pk_mul_f32 v[128:129], v[218:219], v[150:151] op_sel_hi:[1,0]
	v_pk_mul_f32 v[130:131], v[216:217], v[150:151] op_sel_hi:[1,0]
	v_pk_mul_f32 v[128:129], v[186:187], v[128:129]
	v_pk_mul_f32 v[130:131], v[184:185], v[130:131]
	v_pk_mul_f32 v[136:137], v[182:183], v[136:137]
	v_cvt_pk_bf16_f32 v128, v128, v129
	v_cvt_pk_bf16_f32 v129, v130, v131
	s_nop 0
	v_cvt_pk_bf16_f32 v130, v136, v137
	v_cvt_pk_bf16_f32 v131, v138, v139
	global_store_dwordx4 v[134:135], v[128:131], off offset:64

.LBB0_1137:
	v_cmp_gt_i64_e32 vcc, s[8:9], v[10:11]
	s_mov_b64 s[10:11], -1
	s_cbranch_vccnz .LBB0_1136
	s_ashr_i32 s10, s8, 31
	s_lshr_b32 s10, s10, 29
	s_add_i32 s10, s8, s10
	s_ashr_i32 s11, s10, 3
	s_and_b32 s10, s10, -8
	s_sub_i32 s10, s8, s10
	s_cmp_lt_i32 s10, 0
	s_cselect_b32 s27, s24, 0x160
	s_mul_i32 s10, s10, s27
	s_add_i32 s10, s10, s11
	s_mul_hi_i32 s11, s10, 0x2e8ba2e9
	s_lshr_b32 s27, s11, 31
	s_ashr_i32 s11, s11, 4
	s_add_i32 s11, s11, s27
	s_lshl_b32 s27, s11, 2
	s_sub_i32 s33, 0x80, s27
	s_min_i32 s33, s33, 4
	s_mulk_i32 s11, 0x58
	s_sub_i32 s10, s10, s11
	v_cmp_lt_i32_e32 vcc, v19, v169
	s_and_b32 s10, s10, 3
	s_add_i32 s27, s27, s10
	v_cndmask_b32_e32 v28, v168, v19, vcc
	v_lshl_add_u32 v20, s27, 8, v16
	s_waitcnt lgkmcnt(0)
	v_ashrrev_i32_e32 v21, 31, v20
	v_lshlrev_b64 v[20:21], 6, v[20:21]
	v_lshl_add_u64 v[24:25], v[8:9], 0, v[20:21]
	global_load_dwordx4 v[20:23], v[24:25], off
	s_nop 0
	global_load_dwordx4 v[24:27], v[24:25], off offset:16
	s_waitcnt vmcnt(0)
	v_add_f32_e32 v20, v20, v21
	v_add_f32_e32 v21, v22, v23
	v_add_f32_e32 v22, v24, v25
	v_add_f32_e32 v23, v26, v27
	v_add_f32_e32 v20, v20, v21
	v_add_f32_e32 v21, v22, v23
	v_add_f32_e32 v20, v20, v21
	v_lshlrev_b32_e32 v21, 2, v28
	s_nop 1
	v_mov_b32_dpp v21, v20 quad_perm:[1,0,3,2] row_mask:0xf bank_mask:0xf
	s_and_saveexec_b64 s[10:11], s[4:5]
	s_cbranch_execz .LBB0_1135
	s_waitcnt lgkmcnt(0)
	v_add_f32_e32 v20, v20, v21
	v_fmamk_f32 v20, v20, 0x3a800000, v18
	v_rsq_f32_e32 v20, v20
	v_add_u32_e32 v21, s26, v17
	ds_write_b32 v21, v20 offset:14336
	s_branch .LBB0_1135

.LBB0_1749:
	v_cmp_gt_i64_e32 vcc, s[8:9], v[10:11]
	s_mov_b64 s[10:11], -1
	s_cbranch_vccnz .LBB0_1748
	s_ashr_i32 s10, s8, 31
	s_lshr_b32 s10, s10, 29
	s_add_i32 s10, s8, s10
	s_ashr_i32 s11, s10, 3
	s_and_b32 s10, s10, -8
	s_sub_i32 s10, s8, s10
	s_cmp_lt_i32 s10, 0
	s_cselect_b32 s27, s24, 0xc0
	s_mul_i32 s10, s10, s27
	s_add_i32 s10, s10, s11
	s_mul_hi_i32 s11, s10, 0x2aaaaaab
	s_lshr_b32 s27, s11, 31
	s_ashr_i32 s11, s11, 3
	s_add_i32 s11, s11, s27
	s_lshl_b32 s27, s11, 2
	s_sub_i32 s33, 0x80, s27
	s_min_i32 s33, s33, 4
	s_mul_i32 s11, s11, 48
	s_sub_i32 s10, s10, s11
	v_cmp_lt_i32_e32 vcc, v19, v175
	s_and_b32 s10, s10, 3
	s_add_i32 s27, s27, s10
	v_cndmask_b32_e32 v28, v174, v19, vcc
	v_lshl_add_u32 v20, s27, 8, v16
	s_waitcnt lgkmcnt(0)
	v_ashrrev_i32_e32 v21, 31, v20
	v_lshlrev_b64 v[20:21], 6, v[20:21]
	v_lshl_add_u64 v[24:25], v[8:9], 0, v[20:21]
	global_load_dwordx4 v[20:23], v[24:25], off
	s_nop 0
	global_load_dwordx4 v[24:27], v[24:25], off offset:16
	s_waitcnt vmcnt(0)
	v_add_f32_e32 v20, v20, v21
	v_add_f32_e32 v21, v22, v23
	v_add_f32_e32 v22, v24, v25
	v_add_f32_e32 v23, v26, v27
	v_add_f32_e32 v20, v20, v21
	v_add_f32_e32 v21, v22, v23
	v_add_f32_e32 v20, v20, v21
	v_lshlrev_b32_e32 v21, 2, v28
	s_nop 1
	v_mov_b32_dpp v21, v20 quad_perm:[1,0,3,2] row_mask:0xf bank_mask:0xf
	s_and_saveexec_b64 s[10:11], s[4:5]
	s_cbranch_execz .LBB0_1747
	s_waitcnt lgkmcnt(0)
	v_add_f32_e32 v20, v20, v21
	v_fmamk_f32 v20, v20, 0x3a800000, v18
	v_rsq_f32_e32 v20, v20
	v_add_u32_e32 v21, s26, v17
	ds_write_b32 v21, v20 offset:14336
	s_branch .LBB0_1747
